# s_sleep 38 pacing at the top of each P0 weight-transposer iteration (less memory-queue pressure), on top of h1pf
# speedup vs baseline: 1.0066x; 1.0066x over previous
; __device__ __forceinline__ void p0_prologue(const Ptrs& P, LAS unsigned char* lds, int vcu, int G, int tid) {
;     ...
;         for (int it = gw; it < NITEMS; it += NGW) {
;             const int nit = it + NGW; const bool has_n = nit < NITEMS;
;             f32x4 nv[8];
;             const TItem nxt = t_decode(P, has_n ? nit : it, lane); t_load(nxt, nv);
.LBB0_39:
	s_sleep 38
	s_mov_b32 s20, s50
	s_add_i32 s50, s50, s0
	s_cmp_gt_i32 s50, 0xffff
	s_cselect_b64 s[22:23], -1, 0
	s_cmp_lt_i32 s50, 0x10000
	s_cselect_b32 s53, s50, s20
	s_cmpk_gt_i32 s53, 0x3fff
	s_cbranch_scc0 .LBB0_52
	s_add_i32 s20, s53, 0xffffc000
	s_mul_hi_u32 s24, s20, 0xaaaaaaab
	s_lshr_b32 s29, s24, 9
	s_mul_i32 s24, s29, 0x300
	s_sub_i32 s28, s20, s24
	s_lshl_b32 s20, s28, 5
	s_cmpk_gt_u32 s28, 0x1ff
	s_cselect_b64 s[24:25], -1, 0
	s_mov_b64 s[26:27], -1
	s_and_b64 vcc, exec, s[24:25]
	s_cbranch_vccz .LBB0_42
	s_lshl_b32 s26, s28, 10
	s_and_b32 s26, s26, 0x1000
	s_lshl_b32 s27, s28, 4
	s_and_b32 s52, s20, 0x60
	s_and_b32 s27, s27, 0x3f80
	s_or_b32 s26, s52, s26
	s_add_i32 s26, s26, s27
	v_add_u32_e32 v68, s26, v83
	s_mov_b64 s[26:27], 0
